# last-layer epilogue pass 2: dead denormal rescue around v_rsq_f32 removed too (bit-exact)
# baseline (speedup 1.0000x reference)
.LBB0_818:
	s_or_b64 exec, exec, s[34:35]
	s_barrier
	v_lshl_add_u64 v[140:141], v[140:141], 2, s[18:19]
	global_load_dword v218, v[112:113], off sc1
	global_load_dword v219, v[148:149], off sc1
	global_load_dword v220, v[154:155], off sc1
	global_load_dword v221, v[158:159], off sc1
	global_load_dword v222, v[112:113], off offset:512 sc1
	global_load_dword v223, v[112:113], off offset:576 sc1
	global_load_dword v230, v[112:113], off offset:640 sc1
	global_load_dword v231, v[112:113], off offset:704 sc1
	global_load_dwordx4 v[202:205], v[140:141], off
	global_load_dwordx4 v[206:209], v[140:141], off offset:16
	global_load_dwordx4 v[210:213], v[140:141], off offset:512
	global_load_dwordx4 v[214:217], v[140:141], off offset:528
	s_waitcnt vmcnt(0)
	v_mov_b32_e32 v152, v218
	v_mov_b64_e32 v[172:173], v[202:203]
	v_mov_b64_e32 v[174:175], v[204:205]
	v_mov_b64_e32 v[176:177], v[206:207]
	v_mov_b64_e32 v[178:179], v[208:209]
	s_mov_b64 s[34:35], -1
	v_fmamk_f32 v152, v152, 0x3a800000, v192
	s_nop 1
	v_rsq_f32_e32 v152, v152
	s_nop 0
	v_pk_mul_f32 v[124:125], v[124:125], v[152:153] op_sel_hi:[1,0]
	v_pk_mul_f32 v[126:127], v[126:127], v[152:153] op_sel_hi:[1,0]
	v_pk_mul_f32 v[166:167], v[120:121], v[152:153] op_sel_hi:[1,0]
	v_pk_mul_f32 v[180:181], v[122:123], v[152:153] op_sel_hi:[1,0]
	v_pk_mul_f32 v[122:123], v[174:175], v[126:127]
	v_pk_mul_f32 v[120:121], v[172:173], v[124:125]
	v_pk_mul_f32 v[126:127], v[178:179], v[180:181]
	v_pk_mul_f32 v[124:125], v[176:177], v[166:167]
	global_store_dwordx4 v[138:139], v[120:123], off
	global_store_dwordx4 v[138:139], v[124:127], off offset:16
	v_mov_b64_e32 v[120:121], v[210:211]
	v_mov_b64_e32 v[122:123], v[212:213]
	s_nop 0
	v_mov_b64_e32 v[124:125], v[214:215]
	v_mov_b64_e32 v[126:127], v[216:217]
	v_pk_mul_f32 v[142:143], v[142:143], v[152:153] op_sel_hi:[1,0]
	v_pk_mul_f32 v[144:145], v[144:145], v[152:153] op_sel_hi:[1,0]
	v_pk_mul_f32 v[166:167], v[116:117], v[152:153] op_sel_hi:[1,0]
	v_pk_mul_f32 v[152:153], v[118:119], v[152:153] op_sel_hi:[1,0]
	v_pk_mul_f32 v[116:117], v[120:121], v[144:145]
	v_pk_mul_f32 v[118:119], v[122:123], v[142:143]
	v_pk_mul_f32 v[120:121], v[124:125], v[152:153]
	v_pk_mul_f32 v[122:123], v[126:127], v[166:167]
	global_store_dwordx4 v[138:139], v[116:119], off offset:512
	global_store_dwordx4 v[138:139], v[120:123], off offset:528
	v_mov_b32_e32 v124, v219
	s_nop 0
	v_mov_b64_e32 v[116:117], v[202:203]
	v_mov_b64_e32 v[118:119], v[204:205]
	v_mov_b64_e32 v[120:121], v[206:207]
	v_mov_b64_e32 v[122:123], v[208:209]
	v_fmamk_f32 v124, v124, 0x3a800000, v192
	s_nop 1
	v_rsq_f32_e32 v124, v124
	s_nop 0
	v_pk_mul_f32 v[108:109], v[108:109], v[124:125] op_sel_hi:[1,0]
	v_pk_mul_f32 v[110:111], v[110:111], v[124:125] op_sel_hi:[1,0]
	v_pk_mul_f32 v[126:127], v[104:105], v[124:125] op_sel_hi:[1,0]
	v_pk_mul_f32 v[138:139], v[106:107], v[124:125] op_sel_hi:[1,0]
	v_pk_mul_f32 v[106:107], v[118:119], v[110:111]
	v_pk_mul_f32 v[104:105], v[116:117], v[108:109]
	v_pk_mul_f32 v[110:111], v[122:123], v[138:139]
	v_pk_mul_f32 v[108:109], v[120:121], v[126:127]
	global_store_dwordx4 v[114:115], v[104:107], off
	global_store_dwordx4 v[114:115], v[108:111], off offset:16
	v_mov_b64_e32 v[104:105], v[210:211]
	v_mov_b64_e32 v[106:107], v[212:213]
	s_nop 0
	v_mov_b64_e32 v[108:109], v[214:215]
	v_mov_b64_e32 v[110:111], v[216:217]
	v_pk_mul_f32 v[102:103], v[102:103], v[124:125] op_sel_hi:[1,0]
	v_pk_mul_f32 v[116:117], v[146:147], v[124:125] op_sel_hi:[1,0]
	v_pk_mul_f32 v[118:119], v[98:99], v[124:125] op_sel_hi:[1,0]
	v_pk_mul_f32 v[120:121], v[100:101], v[124:125] op_sel_hi:[1,0]
	v_pk_mul_f32 v[98:99], v[104:105], v[116:117]
	v_pk_mul_f32 v[100:101], v[106:107], v[102:103]
	v_pk_mul_f32 v[102:103], v[108:109], v[120:121]
	v_pk_mul_f32 v[104:105], v[110:111], v[118:119]
	global_store_dwordx4 v[114:115], v[98:101], off offset:512
	global_store_dwordx4 v[114:115], v[102:105], off offset:528
	v_mov_b32_e32 v106, v220
	s_nop 0
	v_mov_b64_e32 v[98:99], v[202:203]
	v_mov_b64_e32 v[100:101], v[204:205]
	v_mov_b64_e32 v[102:103], v[206:207]
	v_mov_b64_e32 v[104:105], v[208:209]
	v_fmamk_f32 v106, v106, 0x3a800000, v192
	s_nop 1
	v_rsq_f32_e32 v106, v106
	s_nop 0
	v_pk_mul_f32 v[92:93], v[92:93], v[106:107] op_sel_hi:[1,0]
	v_pk_mul_f32 v[94:95], v[94:95], v[106:107] op_sel_hi:[1,0]
	v_pk_mul_f32 v[108:109], v[88:89], v[106:107] op_sel_hi:[1,0]
	v_pk_mul_f32 v[110:111], v[90:91], v[106:107] op_sel_hi:[1,0]
	v_pk_mul_f32 v[90:91], v[100:101], v[94:95]
	v_pk_mul_f32 v[88:89], v[98:99], v[92:93]
	v_pk_mul_f32 v[94:95], v[104:105], v[110:111]
	v_pk_mul_f32 v[92:93], v[102:103], v[108:109]
	global_store_dwordx4 v[96:97], v[88:91], off
	global_store_dwordx4 v[96:97], v[92:95], off offset:16
	v_mov_b64_e32 v[88:89], v[210:211]
	v_mov_b64_e32 v[90:91], v[212:213]
	s_nop 0
	v_mov_b64_e32 v[92:93], v[214:215]
	v_mov_b64_e32 v[94:95], v[216:217]
	v_pk_mul_f32 v[86:87], v[86:87], v[106:107] op_sel_hi:[1,0]
	v_pk_mul_f32 v[98:99], v[150:151], v[106:107] op_sel_hi:[1,0]
	v_pk_mul_f32 v[100:101], v[82:83], v[106:107] op_sel_hi:[1,0]
	v_pk_mul_f32 v[102:103], v[84:85], v[106:107] op_sel_hi:[1,0]
	v_pk_mul_f32 v[82:83], v[88:89], v[98:99]
	v_pk_mul_f32 v[84:85], v[90:91], v[86:87]
	v_pk_mul_f32 v[86:87], v[92:93], v[102:103]
	v_pk_mul_f32 v[88:89], v[94:95], v[100:101]
	global_store_dwordx4 v[96:97], v[82:85], off offset:512
	global_store_dwordx4 v[96:97], v[86:89], off offset:528
	v_mov_b32_e32 v90, v221
	s_nop 0
	v_mov_b64_e32 v[82:83], v[202:203]
	v_mov_b64_e32 v[84:85], v[204:205]
	v_mov_b64_e32 v[86:87], v[206:207]
	v_mov_b64_e32 v[88:89], v[208:209]
	v_fmamk_f32 v90, v90, 0x3a800000, v192
	s_nop 1
	v_rsq_f32_e32 v90, v90
	s_nop 0
	v_pk_mul_f32 v[76:77], v[76:77], v[90:91] op_sel_hi:[1,0]
	v_pk_mul_f32 v[78:79], v[78:79], v[90:91] op_sel_hi:[1,0]
	v_pk_mul_f32 v[92:93], v[72:73], v[90:91] op_sel_hi:[1,0]
	v_pk_mul_f32 v[94:95], v[74:75], v[90:91] op_sel_hi:[1,0]
	v_pk_mul_f32 v[74:75], v[84:85], v[78:79]
	v_pk_mul_f32 v[72:73], v[82:83], v[76:77]
	v_pk_mul_f32 v[78:79], v[88:89], v[94:95]
	v_pk_mul_f32 v[76:77], v[86:87], v[92:93]
	global_store_dwordx4 v[80:81], v[72:75], off
	global_store_dwordx4 v[80:81], v[76:79], off offset:16
	v_mov_b64_e32 v[72:73], v[210:211]
	v_mov_b64_e32 v[74:75], v[212:213]
	s_nop 0
	v_mov_b64_e32 v[76:77], v[214:215]
	v_mov_b64_e32 v[78:79], v[216:217]
	v_pk_mul_f32 v[70:71], v[70:71], v[90:91] op_sel_hi:[1,0]
	v_pk_mul_f32 v[82:83], v[156:157], v[90:91] op_sel_hi:[1,0]
	v_pk_mul_f32 v[84:85], v[66:67], v[90:91] op_sel_hi:[1,0]
	v_pk_mul_f32 v[86:87], v[68:69], v[90:91] op_sel_hi:[1,0]
	v_pk_mul_f32 v[66:67], v[72:73], v[82:83]
	v_pk_mul_f32 v[68:69], v[74:75], v[70:71]
	v_pk_mul_f32 v[70:71], v[76:77], v[86:87]
	v_pk_mul_f32 v[72:73], v[78:79], v[84:85]
	global_store_dwordx4 v[80:81], v[66:69], off offset:512
	global_store_dwordx4 v[80:81], v[70:73], off offset:528
	v_mov_b32_e32 v74, v222
	s_nop 0
	v_mov_b64_e32 v[66:67], v[202:203]
	v_mov_b64_e32 v[68:69], v[204:205]
	v_mov_b64_e32 v[70:71], v[206:207]
	v_mov_b64_e32 v[72:73], v[208:209]
	v_fmamk_f32 v74, v74, 0x3a800000, v192
	s_nop 1
	v_rsq_f32_e32 v74, v74
	s_nop 0
	v_pk_mul_f32 v[60:61], v[60:61], v[74:75] op_sel_hi:[1,0]
	v_pk_mul_f32 v[62:63], v[62:63], v[74:75] op_sel_hi:[1,0]
	v_pk_mul_f32 v[76:77], v[56:57], v[74:75] op_sel_hi:[1,0]
	v_pk_mul_f32 v[78:79], v[58:59], v[74:75] op_sel_hi:[1,0]
	v_pk_mul_f32 v[58:59], v[68:69], v[62:63]
	v_pk_mul_f32 v[56:57], v[66:67], v[60:61]
	v_pk_mul_f32 v[62:63], v[72:73], v[78:79]
	v_pk_mul_f32 v[60:61], v[70:71], v[76:77]
	global_store_dwordx4 v[64:65], v[56:59], off
	global_store_dwordx4 v[64:65], v[60:63], off offset:16
	v_mov_b64_e32 v[56:57], v[210:211]
	v_mov_b64_e32 v[58:59], v[212:213]
	s_nop 0
	v_mov_b64_e32 v[60:61], v[214:215]
	v_mov_b64_e32 v[62:63], v[216:217]
	v_pk_mul_f32 v[54:55], v[54:55], v[74:75] op_sel_hi:[1,0]
	v_pk_mul_f32 v[66:67], v[160:161], v[74:75] op_sel_hi:[1,0]
	v_pk_mul_f32 v[68:69], v[50:51], v[74:75] op_sel_hi:[1,0]
	v_pk_mul_f32 v[70:71], v[52:53], v[74:75] op_sel_hi:[1,0]
	v_pk_mul_f32 v[50:51], v[56:57], v[66:67]
	v_pk_mul_f32 v[52:53], v[58:59], v[54:55]
	v_pk_mul_f32 v[54:55], v[60:61], v[70:71]
	v_pk_mul_f32 v[56:57], v[62:63], v[68:69]
	global_store_dwordx4 v[64:65], v[50:53], off offset:512
	global_store_dwordx4 v[64:65], v[54:57], off offset:528
	v_mov_b32_e32 v58, v223
	s_nop 0
	v_mov_b64_e32 v[50:51], v[202:203]
	v_mov_b64_e32 v[52:53], v[204:205]
	v_mov_b64_e32 v[54:55], v[206:207]
	v_mov_b64_e32 v[56:57], v[208:209]
	v_fmamk_f32 v58, v58, 0x3a800000, v192
	s_nop 1
	v_rsq_f32_e32 v58, v58
	s_nop 0
	v_pk_mul_f32 v[44:45], v[44:45], v[58:59] op_sel_hi:[1,0]
	v_pk_mul_f32 v[46:47], v[46:47], v[58:59] op_sel_hi:[1,0]
	v_pk_mul_f32 v[60:61], v[40:41], v[58:59] op_sel_hi:[1,0]
	v_pk_mul_f32 v[62:63], v[42:43], v[58:59] op_sel_hi:[1,0]
	v_pk_mul_f32 v[42:43], v[52:53], v[46:47]
	v_pk_mul_f32 v[40:41], v[50:51], v[44:45]
	v_pk_mul_f32 v[46:47], v[56:57], v[62:63]
	v_pk_mul_f32 v[44:45], v[54:55], v[60:61]
	global_store_dwordx4 v[48:49], v[40:43], off
	global_store_dwordx4 v[48:49], v[44:47], off offset:16
	v_mov_b64_e32 v[40:41], v[210:211]
	v_mov_b64_e32 v[42:43], v[212:213]
	s_nop 0
	v_mov_b64_e32 v[44:45], v[214:215]
	v_mov_b64_e32 v[46:47], v[216:217]
	v_pk_mul_f32 v[38:39], v[38:39], v[58:59] op_sel_hi:[1,0]
	v_pk_mul_f32 v[50:51], v[162:163], v[58:59] op_sel_hi:[1,0]
	v_pk_mul_f32 v[52:53], v[34:35], v[58:59] op_sel_hi:[1,0]
	v_pk_mul_f32 v[54:55], v[36:37], v[58:59] op_sel_hi:[1,0]
	v_pk_mul_f32 v[34:35], v[40:41], v[50:51]
	v_pk_mul_f32 v[36:37], v[42:43], v[38:39]
	v_pk_mul_f32 v[38:39], v[44:45], v[54:55]
	v_pk_mul_f32 v[40:41], v[46:47], v[52:53]
	global_store_dwordx4 v[48:49], v[34:37], off offset:512
	global_store_dwordx4 v[48:49], v[38:41], off offset:528
	v_mov_b32_e32 v42, v230
	s_nop 0
	v_mov_b64_e32 v[34:35], v[202:203]
	v_mov_b64_e32 v[36:37], v[204:205]
	v_mov_b64_e32 v[38:39], v[206:207]
	v_mov_b64_e32 v[40:41], v[208:209]
	v_fmamk_f32 v42, v42, 0x3a800000, v192
	s_nop 1
	v_rsq_f32_e32 v42, v42
	s_nop 0
	v_pk_mul_f32 v[28:29], v[28:29], v[42:43] op_sel_hi:[1,0]
	v_pk_mul_f32 v[30:31], v[30:31], v[42:43] op_sel_hi:[1,0]
	v_pk_mul_f32 v[44:45], v[24:25], v[42:43] op_sel_hi:[1,0]
	v_pk_mul_f32 v[46:47], v[26:27], v[42:43] op_sel_hi:[1,0]
	v_pk_mul_f32 v[26:27], v[36:37], v[30:31]
	v_pk_mul_f32 v[24:25], v[34:35], v[28:29]
	v_pk_mul_f32 v[30:31], v[40:41], v[46:47]
	v_pk_mul_f32 v[28:29], v[38:39], v[44:45]
	global_store_dwordx4 v[32:33], v[24:27], off
	global_store_dwordx4 v[32:33], v[28:31], off offset:16
	v_mov_b64_e32 v[24:25], v[210:211]
	v_mov_b64_e32 v[26:27], v[212:213]
	s_nop 0
	v_mov_b64_e32 v[28:29], v[214:215]
	v_mov_b64_e32 v[30:31], v[216:217]
	v_pk_mul_f32 v[22:23], v[22:23], v[42:43] op_sel_hi:[1,0]
	v_pk_mul_f32 v[34:35], v[164:165], v[42:43] op_sel_hi:[1,0]
	v_pk_mul_f32 v[36:37], v[18:19], v[42:43] op_sel_hi:[1,0]
	v_pk_mul_f32 v[38:39], v[20:21], v[42:43] op_sel_hi:[1,0]
	v_pk_mul_f32 v[18:19], v[24:25], v[34:35]
	v_pk_mul_f32 v[20:21], v[26:27], v[22:23]
	v_pk_mul_f32 v[22:23], v[28:29], v[38:39]
	v_pk_mul_f32 v[24:25], v[30:31], v[36:37]
	global_store_dwordx4 v[32:33], v[18:21], off offset:512
	global_store_dwordx4 v[32:33], v[22:25], off offset:528
	v_mov_b32_e32 v26, v231
	s_nop 0
	v_mov_b64_e32 v[18:19], v[202:203]
	v_mov_b64_e32 v[20:21], v[204:205]
	v_mov_b64_e32 v[22:23], v[206:207]
	v_mov_b64_e32 v[24:25], v[208:209]
	v_fmamk_f32 v26, v26, 0x3a800000, v192
	s_nop 1
	v_rsq_f32_e32 v26, v26
	s_nop 0
	v_pk_mul_f32 v[12:13], v[12:13], v[26:27] op_sel_hi:[1,0]
	v_pk_mul_f32 v[14:15], v[14:15], v[26:27] op_sel_hi:[1,0]
	v_pk_mul_f32 v[28:29], v[8:9], v[26:27] op_sel_hi:[1,0]
	v_pk_mul_f32 v[30:31], v[10:11], v[26:27] op_sel_hi:[1,0]
	v_pk_mul_f32 v[10:11], v[20:21], v[14:15]
	v_pk_mul_f32 v[8:9], v[18:19], v[12:13]
	v_pk_mul_f32 v[14:15], v[24:25], v[30:31]
	v_pk_mul_f32 v[12:13], v[22:23], v[28:29]
	global_store_dwordx4 v[16:17], v[8:11], off
	global_store_dwordx4 v[16:17], v[12:15], off offset:16
	v_mov_b64_e32 v[8:9], v[210:211]
	v_mov_b64_e32 v[10:11], v[212:213]
	s_nop 0
	v_mov_b64_e32 v[12:13], v[214:215]
	v_mov_b64_e32 v[14:15], v[216:217]
	v_pk_mul_f32 v[6:7], v[6:7], v[26:27] op_sel_hi:[1,0]
	v_pk_mul_f32 v[4:5], v[4:5], v[26:27] op_sel_hi:[1,0]
	s_andn2_b64 vcc, exec, s[40:41]
	v_pk_mul_f32 v[18:19], v[2:3], v[26:27] op_sel_hi:[1,0]
	v_pk_mul_f32 v[20:21], v[0:1], v[26:27] op_sel_hi:[1,0]
	v_pk_mul_f32 v[0:1], v[8:9], v[4:5]
	v_pk_mul_f32 v[2:3], v[10:11], v[6:7]
	v_pk_mul_f32 v[4:5], v[12:13], v[20:21]
	v_pk_mul_f32 v[6:7], v[14:15], v[18:19]
	global_store_dwordx4 v[16:17], v[0:3], off offset:512
	global_store_dwordx4 v[16:17], v[4:7], off offset:528
	s_cbranch_vccnz .LBB0_779
	s_andn2_b64 vcc, exec, s[10:11]
	s_cbranch_vccnz .LBB0_778
	s_barrier
	s_branch .LBB0_778
